# P5 pre-pass with 6 rows per wave (instead of 12) on the 72 idle workgroups of the SchedC stage
# baseline (speedup 1.0000x reference)
; __device__ __forceinline__ float bf_lo(unsigned w) { return __uint_as_float(w << 16); }
; __device__ __forceinline__ float bf_hi(unsigned w) { return __uint_as_float(w & 0xffff0000u); }
; template <int NR>
; __device__ __forceinline__ void p5_rows(const Params& p, const bf16_t* __restrict__ DL, int r, int nw, int lane) {
;     f32x4 v[NR][8]; u32x4 d[NR][4];
; #pragma unroll
;     for (int k = 0; k < NR; ++k) { const int row = r + k * nw; const float* x = row < TP ? p.xp + (size_t)row * D : p.xs + (size_t)(row - TP) * D;
; #pragma unroll
;         for (int i = 0; i < 4; ++i) { v[k][2 * i] = *(const f32x4*)(x + (i * 64 + lane) * 8); v[k][2 * i + 1] = *(const f32x4*)(x + (i * 64 + lane) * 8 + 4);
;             d[k][i] = *(const u32x4*)(DL + (size_t)row * LDP + (i * 64 + lane) * 8); } }
; #pragma unroll
;     for (int k = 0; k < NR; ++k) { const int row = r + k * nw; float ss = 0.f;
; #pragma unroll
;         for (int i = 0; i < 4; ++i) { const u32x4 w = d[k][i];
;             v[k][2 * i] += (f32x4){bf_lo(w.x), bf_hi(w.x), bf_lo(w.y), bf_hi(w.y)}; v[k][2 * i + 1] += (f32x4){bf_lo(w.z), bf_hi(w.z), bf_lo(w.w), bf_hi(w.w)}; }
; #pragma unroll
;         for (int i = 0; i < 8; ++i) ss += (v[k][i][0] * v[k][i][0] + v[k][i][1] * v[k][i][1]) + (v[k][i][2] * v[k][i][2] + v[k][i][3] * v[k][i][3]);
; #pragma unroll
;         for (int o = 32; o >= 1; o >>= 1) ss += __shfl_xor(ss, o);
;         const float rs = rsqrtf(ss * (1.0f / D) + EPS);
; __device__ __forceinline__ void phase5(const Params& p) {
;     int t_ = threadIdx.x; asm volatile("" : "+v"(t_));
;     const int lane = t_ & 63, gw = blockIdx.x * 8 + (t_ >> 6), nw = gridDim.x * 8;
;     const bf16_t* DL = (const bf16_t*)(p.ws + WS_H);
;     int r = gw;
;     for (; r + nw < T; r += 2 * nw) p5_rows<2>(p, DL, r, nw, lane);
;     if (r < T) p5_rows<1>(p, DL, r, nw, lane);
.Lp5pre_begin:
	v_mov_b32_e32 v232, v0
	s_mov_b32 s0, 0x3000
	v_ashrrev_i32_e32 v95, 6, v0
	v_add_u32_e32 v70, s30, v95
	v_and_b32_e32 v1, 63, v0
	v_add_u32_e32 v6, s74, v70
	v_cmp_gt_i32_e32 vcc, s0, v6
	v_lshlrev_b32_e32 v68, 5, v1
	v_lshlrev_b32_e32 v72, 4, v1
	s_and_saveexec_b64 s[0:1], vcc
	s_cbranch_execz .Lp5pre_1198
	v_lshlrev_b32_e32 v0, 3, v1
	v_mbcnt_hi_u32_b32 v1, -1, v190
	v_and_b32_e32 v3, 64, v1
	v_add_u32_e32 v3, 64, v3
	v_xor_b32_e32 v5, 32, v1
	v_cmp_lt_i32_e32 vcc, v5, v3
	v_or_b32_e32 v2, 0x400, v0
	v_mov_b32_e32 v75, 0
	v_cndmask_b32_e32 v5, v1, v5, vcc
	v_lshlrev_b32_e32 v100, 2, v5
	v_xor_b32_e32 v5, 16, v1
	v_cmp_lt_i32_e32 vcc, v5, v3
	v_or_b32_e32 v4, 0x600, v0
	s_lshl_b32 s2, s33, 4
	v_cndmask_b32_e32 v5, v1, v5, vcc
	v_lshlrev_b32_e32 v101, 2, v5
	v_xor_b32_e32 v5, 8, v1
	v_cmp_lt_i32_e32 vcc, v5, v3
	v_lshlrev_b32_e32 v74, 2, v2
	v_ashrrev_i32_e32 v71, 31, v70
	v_cndmask_b32_e32 v5, v1, v5, vcc
	v_lshlrev_b32_e32 v102, 2, v5
	v_xor_b32_e32 v5, 4, v1
	v_cmp_lt_i32_e32 vcc, v5, v3
	v_mov_b32_e32 v69, v75
	v_lshl_add_u64 v[78:79], s[22:23], 0, v[74:75]
	v_cndmask_b32_e32 v5, v1, v5, vcc
	v_lshlrev_b32_e32 v103, 2, v5
	v_xor_b32_e32 v5, 2, v1
	v_cmp_lt_i32_e32 vcc, v5, v3
	v_lshlrev_b32_e32 v74, 2, v4
	v_mov_b32_e32 v73, v75
	v_cndmask_b32_e32 v5, v1, v5, vcc
	v_lshlrev_b32_e32 v104, 2, v5
	v_xor_b32_e32 v5, 1, v1
	v_cmp_lt_i32_e32 vcc, v5, v3
	s_ashr_i32 s3, s2, 31
	v_lshlrev_b64 v[8:9], 13, v[70:71]
	v_cndmask_b32_e32 v1, v1, v5, vcc
	v_lshlrev_b32_e32 v86, 2, v2
	v_lshlrev_b32_e32 v88, 2, v4
	v_lshlrev_b32_e32 v105, 2, v1
	v_lshl_add_u64 v[76:77], s[22:23], 0, v[68:69]
	v_lshl_add_u64 v[80:81], s[22:23], 0, v[74:75]
	v_lshl_add_u64 v[82:83], s[26:27], 0, v[72:73]
	v_lshl_add_u64 v[84:85], s[36:37], 0, v[8:9]
	s_lshl_b64 s[4:5], s[2:3], 13
	s_add_i32 s9, s74, s30
	s_mov_b64 s[6:7], 0
	s_movk_i32 s12, 0x7fff
	s_movk_i32 s13, 0x1080
	s_mov_b32 s8, 0x3a000000
	s_mov_b32 s14, 0x800000
	s_mov_b32 s15, 0x2fff
	v_lshlrev_b32_e32 v74, 2, v0
	v_mov_b32_e32 v90, v86
	v_mov_b32_e32 v91, v75
	v_mov_b32_e32 v92, v88
	v_mov_b32_e32 v93, v75
	v_mov_b32_e32 v94, 0x358637bd
	s_branch .Lp5pre_1191

; __device__ __forceinline__ void phase5(const Params& p) {
;     int t_ = threadIdx.x; asm volatile("" : "+v"(t_));
;     const int lane = t_ & 63, gw = blockIdx.x * 8 + (t_ >> 6), nw = gridDim.x * 8;
;     const bf16_t* DL = (const bf16_t*)(p.ws + WS_H);
;     int r = gw;
;     for (; r + nw < T; r += 2 * nw) p5_rows<2>(p, DL, r, nw, lane);
;     if (r < T) p5_rows<1>(p, DL, r, nw, lane);
.LBB0_1188:
	s_or_b64 exec, exec, s[2:3]
	s_waitcnt lgkmcnt(0)
	s_barrier
	s_mov_b32 s0, 0x8800
	v_ashrrev_i32_e32 v95, 6, v0
	s_mul_i32 s1, s74, 6
	s_cmpk_gt_u32 s30, 0x5bf
	s_cselect_b32 s1, s1, 0
	s_cmpk_eq_u32 s33, 0x100
	s_cselect_b32 s1, s1, 0
	s_nop 0
	v_add_u32_e32 v95, s1, v95
	v_add_u32_e32 v70, s30, v95
	v_and_b32_e32 v1, 63, v0
	v_add_u32_e32 v6, s74, v70
	v_cmp_gt_i32_e32 vcc, s0, v6
	v_lshlrev_b32_e32 v68, 5, v1
	v_lshlrev_b32_e32 v72, 4, v1
	s_and_saveexec_b64 s[0:1], vcc
	s_cbranch_execz .LBB0_1198
	v_lshlrev_b32_e32 v0, 3, v1
	v_mbcnt_hi_u32_b32 v1, -1, v190
	v_and_b32_e32 v3, 64, v1
	v_add_u32_e32 v3, 64, v3
	v_xor_b32_e32 v5, 32, v1
	v_cmp_lt_i32_e32 vcc, v5, v3
	v_or_b32_e32 v2, 0x400, v0
	v_mov_b32_e32 v75, 0
	v_cndmask_b32_e32 v5, v1, v5, vcc
	v_lshlrev_b32_e32 v100, 2, v5
	v_xor_b32_e32 v5, 16, v1
	v_cmp_lt_i32_e32 vcc, v5, v3
	v_or_b32_e32 v4, 0x600, v0
	s_lshl_b32 s2, s33, 4
	v_cndmask_b32_e32 v5, v1, v5, vcc
	v_lshlrev_b32_e32 v101, 2, v5
	v_xor_b32_e32 v5, 8, v1
	v_cmp_lt_i32_e32 vcc, v5, v3
	v_lshlrev_b32_e32 v74, 2, v2
	v_ashrrev_i32_e32 v71, 31, v70
	v_cndmask_b32_e32 v5, v1, v5, vcc
	v_lshlrev_b32_e32 v102, 2, v5
	v_xor_b32_e32 v5, 4, v1
	v_cmp_lt_i32_e32 vcc, v5, v3
	v_mov_b32_e32 v69, v75
	v_lshl_add_u64 v[78:79], s[22:23], 0, v[74:75]
	v_cndmask_b32_e32 v5, v1, v5, vcc
	v_lshlrev_b32_e32 v103, 2, v5
	v_xor_b32_e32 v5, 2, v1
	v_cmp_lt_i32_e32 vcc, v5, v3
	v_lshlrev_b32_e32 v74, 2, v4
	v_mov_b32_e32 v73, v75
	v_cndmask_b32_e32 v5, v1, v5, vcc
	v_lshlrev_b32_e32 v104, 2, v5
	v_xor_b32_e32 v5, 1, v1
	v_cmp_lt_i32_e32 vcc, v5, v3
	s_ashr_i32 s3, s2, 31
	v_lshlrev_b64 v[8:9], 13, v[70:71]
	v_cndmask_b32_e32 v1, v1, v5, vcc
	v_lshlrev_b32_e32 v86, 2, v2
	v_lshlrev_b32_e32 v88, 2, v4
	v_lshlrev_b32_e32 v105, 2, v1
	v_lshl_add_u64 v[76:77], s[22:23], 0, v[68:69]
	v_lshl_add_u64 v[80:81], s[22:23], 0, v[74:75]
	v_lshl_add_u64 v[82:83], s[26:27], 0, v[72:73]
	v_lshl_add_u64 v[84:85], s[36:37], 0, v[8:9]
	s_lshl_b64 s[4:5], s[2:3], 13
	s_add_i32 s9, s74, s30
	s_mov_b64 s[6:7], 0
	s_movk_i32 s12, 0x7fff
	s_movk_i32 s13, 0x1080
	s_mov_b32 s8, 0x3a000000
	s_mov_b32 s14, 0x800000
	s_mov_b32 s15, 0x87ff
	v_lshlrev_b32_e32 v74, 2, v0
	v_mov_b32_e32 v90, v86
	v_mov_b32_e32 v91, v75
	v_mov_b32_e32 v92, v88
	v_mov_b32_e32 v93, v75
	v_mov_b32_e32 v94, 0x358637bd
	s_branch .LBB0_1191
